# P7 + grid barrier SEAM(7) folded: each workgroup computes rstd only for the 4 token tiles its own P8 units use, then a workgroup barrier (fallback to the original path if G != 256)
# speedup vs baseline: 1.0106x; 1.0106x over previous
; #define SEAM(k) do { if (IN(k) && IN((k) + 1)) xcd_barrier(xbar); } while (0)
; __device__ __forceinline__ float rstd_from_partials(const float* part, int row) {
;     const f32x4* p = (const f32x4*)(part + (size_t)row * 16); const f32x4 a = p[0], b = p[1], c = p[2], d = p[3];
;     const float s = ((a[0] + a[1]) + (a[2] + a[3])) + ((b[0] + b[1]) + (b[2] + b[3])) + ((c[0] + c[1]) + (c[2] + c[3])) + ((d[0] + d[1]) + (d[2] + d[3]));
;     return __builtin_amdgcn_rsqf(s * (1.0f / 1024.0f) + 1e-6f);
; }
; __global__ void __launch_bounds__(512) fwd_kernel(Args args) {
;     ...
;     if (IN(7)) { for (int m = F.bid * 512 + F.tid; m < MTOK; m += F.G * 512) rstd[m] = pg8::rstd_from_partials(part, m); }
;     SEAM(7);
.LBB0_737:
	s_cmp_lt_i32 s72, 8
	s_cselect_b64 s[4:5], -1, 0
	s_and_b64 s[4:5], s[4:5], s[0:1]
	s_andn2_b64 vcc, exec, s[4:5]
	s_cbranch_vccnz .LBB0_742
	s_cmp_lg_u32 s74, 0x100
	s_cbranch_scc1 .Lp7_orig
	s_cmp_gt_i32 s73, 8
	s_cbranch_scc0 .Lp7_orig
	s_waitcnt lgkmcnt(0)
	s_and_b32 s6, s2, 7
	s_lshr_b32 s7, s2, 3
	s_lshl_b32 s6, s6, 4
	s_and_b32 s8, s7, 7
	s_lshr_b32 s7, s7, 2
	s_add_i32 s8, s8, s6
	s_add_i32 s7, s7, s6
	v_lshrrev_b32_e32 v0, 7, v221
	v_mov_b32_e32 v1, s8
	v_mov_b32_e32 v2, s7
	v_cmp_gt_u32_e32 vcc, 2, v0
	s_nop 1
	v_cndmask_b32_e32 v1, v2, v1, vcc
	v_and_b32_e32 v2, 1, v0
	v_lshl_add_u32 v1, v2, 3, v1
	v_and_b32_e32 v2, 0x7f, v221
	v_lshlrev_b32_e32 v2, 1, v2
	v_lshl_add_u32 v0, v1, 8, v2
	v_lshlrev_b32_e32 v4, 6, v0
	global_load_dwordx4 v[6:9], v4, s[70:71] offset:0
	global_load_dwordx4 v[10:13], v4, s[70:71] offset:16
	global_load_dwordx4 v[14:17], v4, s[70:71] offset:32
	global_load_dwordx4 v[18:21], v4, s[70:71] offset:48
	global_load_dwordx4 v[22:25], v4, s[70:71] offset:64
	global_load_dwordx4 v[26:29], v4, s[70:71] offset:80
	global_load_dwordx4 v[30:33], v4, s[70:71] offset:96
	global_load_dwordx4 v[34:37], v4, s[70:71] offset:112
	v_mov_b32_e32 v1, 0x358637bd
	v_lshlrev_b32_e32 v5, 2, v0
	v_add_u32_e32 v5, 0x200000, v5
	s_waitcnt vmcnt(4)
	v_add_f32_e32 v6, v6, v7
	v_add_f32_e32 v8, v8, v9
	v_add_f32_e32 v6, v6, v8
	v_add_f32_e32 v10, v10, v11
	v_add_f32_e32 v12, v12, v13
	v_add_f32_e32 v10, v10, v12
	v_add_f32_e32 v14, v14, v15
	v_add_f32_e32 v16, v16, v17
	v_add_f32_e32 v14, v14, v16
	v_add_f32_e32 v18, v18, v19
	v_add_f32_e32 v20, v20, v21
	v_add_f32_e32 v18, v18, v20
	v_add_f32_e32 v6, v6, v10
	v_add_f32_e32 v6, v6, v14
	v_add_f32_e32 v6, v6, v18
	s_waitcnt vmcnt(0)
	v_add_f32_e32 v22, v22, v23
	v_add_f32_e32 v24, v24, v25
	v_add_f32_e32 v22, v22, v24
	v_add_f32_e32 v26, v26, v27
	v_add_f32_e32 v28, v28, v29
	v_add_f32_e32 v26, v26, v28
	v_add_f32_e32 v30, v30, v31
	v_add_f32_e32 v32, v32, v33
	v_add_f32_e32 v30, v30, v32
	v_add_f32_e32 v34, v34, v35
	v_add_f32_e32 v36, v36, v37
	v_add_f32_e32 v34, v34, v36
	v_add_f32_e32 v22, v22, v26
	v_add_f32_e32 v22, v22, v30
	v_add_f32_e32 v22, v22, v34
	v_fmamk_f32 v6, v6, 0x3a800000, v1
	v_fmamk_f32 v7, v22, 0x3a800000, v1
	v_rsq_f32_e32 v6, v6
	v_rsq_f32_e32 v7, v7
	s_nop 0
	global_store_dwordx2 v5, v[6:7], s[70:71]
	s_waitcnt vmcnt(0)
	s_barrier
	s_cmp_gt_i32 s73, 8
	s_cselect_b64 s[0:1], -1, 0
	s_branch .LBB0_796
.Lp7_orig:
	v_lshl_add_u32 v0, s2, 9, v221
	s_mov_b32 s0, 0x8000
	v_cmp_gt_i32_e32 vcc, s0, v0
	s_and_saveexec_b64 s[0:1], vcc
	s_cbranch_execz .LBB0_741
	s_waitcnt lgkmcnt(0)
	v_ashrrev_i32_e32 v1, 31, v0
	s_lshl_b32 s6, s74, 9
	v_lshlrev_b64 v[4:5], 6, v[0:1]
	v_lshl_add_u64 v[2:3], v[0:1], 2, s[70:71]
	s_mov_b64 s[8:9], 0x200000
	s_ashr_i32 s7, s6, 31
	v_lshl_add_u64 v[4:5], s[70:71], 0, v[4:5]
	v_lshl_add_u64 v[2:3], v[2:3], 0, s[8:9]
	s_lshl_b64 s[8:9], s[6:7], 2
	v_lshl_add_u64 v[4:5], v[4:5], 0, 32
	s_lshl_b64 s[10:11], s[6:7], 6
	s_mov_b64 s[12:13], 0
	v_mov_b32_e32 v1, 0x358637bd
	s_movk_i32 s3, 0x7fff
